# v78 + static s_setprio 1 for waves 0-3 (older half) in the two attention unit loops
# speedup vs baseline: 1.0190x; 1.0190x over previous
.LBB0_229:
	v_lshlrev_b32_e32 v225, 2, v206
	v_add_u32_e32 v225, 0x1b000, v225
	ds_write_b32 v225, v254
	v_readfirstlane_b32 s101, v206
	s_nop 3
	s_lshr_b32 s101, s101, 8
	s_cmp_eq_u32 s101, 0
	s_cbranch_scc0 .Lprio_attn_0
	s_setprio 1
